# v28 plus counted lgkmcnt waits (12/8/4/0) between the LDS transpose reads and the fp8 converts in the MoE weight conversion routine
# speedup vs baseline: 1.0048x; 1.0048x over previous
; #define LAS __attribute__((address_space(3)))
; __device__ __forceinline__ unsigned cvt_pk_bf16(float lo, float hi) { unsigned r; asm volatile("v_cvt_pk_bf16_f32 %0, %1, %2" : "=v"(r) : "v"(lo), "v"(hi)); return r; }
; __device__ __forceinline__ unsigned cvt4_fp8(float a, float b, float c, float d) { unsigned w = __builtin_amdgcn_cvt_pk_fp8_f32(a, b, 0u, false); return (unsigned)__builtin_amdgcn_cvt_pk_fp8_f32(c, d, (int)w, true); }
; #define LDS_WAIT() asm volatile("s_waitcnt lgkmcnt(0)" ::: "memory")
;     ...
;         for (int i = 0; i < 8; ++i) { const int kk = 8 * i + r8; const float m = kscale ? sc * kscale[k0 + kk] : sc;
;             scr[kk * 33 + c4 + 0] = v[i][0] * m; scr[kk * 33 + c4 + 1] = v[i][1] * m; scr[kk * 33 + c4 + 2] = v[i][2] * m; scr[kk * 33 + c4 + 3] = v[i][3] * m; }
;     } else {
;         const float* src; int ld; float sc; f(n0 + (lane & 31), src, ld, sc); sc *= mul;
; #pragma unroll 8
;         for (int i = 0; i < 32; ++i) { const int kk = 2 * i + (lane >> 5); float v = src[(size_t)(k0 + kk) * ld] * sc; if (kscale) v *= kscale[k0 + kk]; scr[kk * 33 + (lane & 31)] = v; }
;     }
;     LDS_WAIT(); asm volatile("" ::: "memory");
;     const int c = lane & 7;
; #pragma unroll
;     for (int j = 0; j < 4; ++j) { const int n = (lane >> 3) + 8 * j; const LAS float* s = scr + (8 * c) * 33 + n;
;         if constexpr (F8OUT) {
;             u32x2 o; o.x = cvt4_fp8(s[0 * 33], s[1 * 33], s[2 * 33], s[3 * 33]); o.y = cvt4_fp8(s[4 * 33], s[5 * 33], s[6 * 33], s[7 * 33]);
;             *(u32x2*)((unsigned char*)WT + (size_t)(n0 + n) * K + k0 + 8 * c) = o;
;         } else {
;             u32x4 o; o.x = cvt_pk_bf16(s[0 * 33], s[1 * 33]); o.y = cvt_pk_bf16(s[2 * 33], s[3 * 33]); o.z = cvt_pk_bf16(s[4 * 33], s[5 * 33]); o.w = cvt_pk_bf16(s[6 * 33], s[7 * 33]);
;             *(u32x4*)(WT + (size_t)(n0 + n) * K + k0 + 8 * c) = o; } }
;     LDS_WAIT(); asm volatile("" ::: "memory");
.Lcve_iB4e:
	s_waitcnt vmcnt(8)
	v_pk_mul_f32 v[24:25], v[24:25], s[32:33] op_sel_hi:[1,0]
	v_pk_mul_f32 v[26:27], v[26:27], s[32:33] op_sel_hi:[1,0]
	ds_write2_b32 v128, v24, v25 offset1:1
	ds_write2_b32 v128, v26, v27 offset0:2 offset1:3
	v_pk_mul_f32 v[28:29], v[28:29], s[32:33] op_sel_hi:[1,0]
	v_pk_mul_f32 v[30:31], v[30:31], s[32:33] op_sel_hi:[1,0]
	ds_write2_b32 v129, v28, v29 offset1:1
	ds_write2_b32 v129, v30, v31 offset0:2 offset1:3
	v_pk_mul_f32 v[32:33], v[32:33], s[32:33] op_sel_hi:[1,0]
	v_pk_mul_f32 v[34:35], v[34:35], s[32:33] op_sel_hi:[1,0]
	ds_write2_b32 v130, v32, v33 offset1:1
	ds_write2_b32 v130, v34, v35 offset0:2 offset1:3
	v_pk_mul_f32 v[36:37], v[36:37], s[32:33] op_sel_hi:[1,0]
	v_pk_mul_f32 v[38:39], v[38:39], s[32:33] op_sel_hi:[1,0]
	ds_write2_b32 v131, v36, v37 offset1:1
	ds_write2_b32 v131, v38, v39 offset0:2 offset1:3
	v_pk_mul_f32 v[40:41], v[40:41], s[32:33] op_sel_hi:[1,0]
	v_pk_mul_f32 v[42:43], v[42:43], s[32:33] op_sel_hi:[1,0]
	ds_write2_b32 v132, v40, v41 offset1:1
	ds_write2_b32 v132, v42, v43 offset0:2 offset1:3
	v_pk_mul_f32 v[44:45], v[44:45], s[32:33] op_sel_hi:[1,0]
	v_pk_mul_f32 v[46:47], v[46:47], s[32:33] op_sel_hi:[1,0]
	ds_write2_b32 v133, v44, v45 offset1:1
	ds_write2_b32 v133, v46, v47 offset0:2 offset1:3
	v_pk_mul_f32 v[48:49], v[48:49], s[32:33] op_sel_hi:[1,0]
	v_pk_mul_f32 v[50:51], v[50:51], s[32:33] op_sel_hi:[1,0]
	ds_write2_b32 v134, v48, v49 offset1:1
	ds_write2_b32 v134, v50, v51 offset0:2 offset1:3
	v_pk_mul_f32 v[52:53], v[52:53], s[32:33] op_sel_hi:[1,0]
	v_pk_mul_f32 v[54:55], v[54:55], s[32:33] op_sel_hi:[1,0]
	ds_write2_b32 v135, v52, v53 offset1:1
	ds_write2_b32 v135, v54, v55 offset0:2 offset1:3
	s_waitcnt lgkmcnt(0)
	ds_read2_b32 v[88:89], v9 offset0:0 offset1:33
	ds_read2_b32 v[90:91], v9 offset0:66 offset1:99
	ds_read2_b32 v[92:93], v9 offset0:132 offset1:165
	ds_read2_b32 v[94:95], v9 offset0:198 offset1:231
	ds_read2_b32 v[96:97], v9 offset0:8 offset1:41
	ds_read2_b32 v[98:99], v9 offset0:74 offset1:107
	ds_read2_b32 v[100:101], v9 offset0:140 offset1:173
	ds_read2_b32 v[102:103], v9 offset0:206 offset1:239
	ds_read2_b32 v[104:105], v9 offset0:16 offset1:49
	ds_read2_b32 v[106:107], v9 offset0:82 offset1:115
	ds_read2_b32 v[108:109], v9 offset0:148 offset1:181
	ds_read2_b32 v[110:111], v9 offset0:214 offset1:247
	ds_read2_b32 v[112:113], v9 offset0:24 offset1:57
	ds_read2_b32 v[114:115], v9 offset0:90 offset1:123
	ds_read2_b32 v[116:117], v9 offset0:156 offset1:189
	ds_read2_b32 v[118:119], v9 offset0:222 offset1:255
	s_waitcnt lgkmcnt(12)
	v_cvt_pk_fp8_f32 v120, v88, v89
	v_cvt_pk_fp8_f32 v121, v92, v93
	v_cvt_pk_fp8_f32 v120, v90, v91 op_sel:[0,0,1]
	v_cvt_pk_fp8_f32 v121, v94, v95 op_sel:[0,0,1]
	s_waitcnt lgkmcnt(8)
	v_cvt_pk_fp8_f32 v122, v96, v97
	v_cvt_pk_fp8_f32 v123, v100, v101
	v_cvt_pk_fp8_f32 v122, v98, v99 op_sel:[0,0,1]
	v_cvt_pk_fp8_f32 v123, v102, v103 op_sel:[0,0,1]
	s_waitcnt lgkmcnt(4)
	v_cvt_pk_fp8_f32 v124, v104, v105
	v_cvt_pk_fp8_f32 v125, v108, v109
	v_cvt_pk_fp8_f32 v124, v106, v107 op_sel:[0,0,1]
	v_cvt_pk_fp8_f32 v125, v110, v111 op_sel:[0,0,1]
	s_waitcnt lgkmcnt(0)
	v_cvt_pk_fp8_f32 v126, v112, v113
	v_cvt_pk_fp8_f32 v127, v116, v117
	v_cvt_pk_fp8_f32 v126, v114, v115 op_sel:[0,0,1]
	v_cvt_pk_fp8_f32 v127, v118, v119 op_sel:[0,0,1]
	s_cmp_eq_u32 s30, 0
	s_cbranch_scc0 .Lcve_pA5d
	global_store_dwordx2 v19, v[120:121], s[28:29]
	global_store_dwordx2 v20, v[122:123], s[28:29]
	global_store_dwordx2 v21, v[124:125], s[28:29]
	global_store_dwordx2 v22, v[126:127], s[28:29]
	s_branch .Lcve_pA5e

; #define LAS __attribute__((address_space(3)))
; __device__ __forceinline__ unsigned cvt_pk_bf16(float lo, float hi) { unsigned r; asm volatile("v_cvt_pk_bf16_f32 %0, %1, %2" : "=v"(r) : "v"(lo), "v"(hi)); return r; }
; __device__ __forceinline__ unsigned cvt4_fp8(float a, float b, float c, float d) { unsigned w = __builtin_amdgcn_cvt_pk_fp8_f32(a, b, 0u, false); return (unsigned)__builtin_amdgcn_cvt_pk_fp8_f32(c, d, (int)w, true); }
; #define LDS_WAIT() asm volatile("s_waitcnt lgkmcnt(0)" ::: "memory")
;     ...
;         for (int i = 0; i < 8; ++i) { const int kk = 8 * i + r8; const float m = kscale ? sc * kscale[k0 + kk] : sc;
;             scr[kk * 33 + c4 + 0] = v[i][0] * m; scr[kk * 33 + c4 + 1] = v[i][1] * m; scr[kk * 33 + c4 + 2] = v[i][2] * m; scr[kk * 33 + c4 + 3] = v[i][3] * m; }
;     } else {
;         const float* src; int ld; float sc; f(n0 + (lane & 31), src, ld, sc); sc *= mul;
; #pragma unroll 8
;         for (int i = 0; i < 32; ++i) { const int kk = 2 * i + (lane >> 5); float v = src[(size_t)(k0 + kk) * ld] * sc; if (kscale) v *= kscale[k0 + kk]; scr[kk * 33 + (lane & 31)] = v; }
;     }
;     LDS_WAIT(); asm volatile("" ::: "memory");
;     const int c = lane & 7;
; #pragma unroll
;     for (int j = 0; j < 4; ++j) { const int n = (lane >> 3) + 8 * j; const LAS float* s = scr + (8 * c) * 33 + n;
;         if constexpr (F8OUT) {
;             u32x2 o; o.x = cvt4_fp8(s[0 * 33], s[1 * 33], s[2 * 33], s[3 * 33]); o.y = cvt4_fp8(s[4 * 33], s[5 * 33], s[6 * 33], s[7 * 33]);
;             *(u32x2*)((unsigned char*)WT + (size_t)(n0 + n) * K + k0 + 8 * c) = o;
;         } else {
;             u32x4 o; o.x = cvt_pk_bf16(s[0 * 33], s[1 * 33]); o.y = cvt_pk_bf16(s[2 * 33], s[3 * 33]); o.z = cvt_pk_bf16(s[4 * 33], s[5 * 33]); o.w = cvt_pk_bf16(s[6 * 33], s[7 * 33]);
;             *(u32x4*)(WT + (size_t)(n0 + n) * K + k0 + 8 * c) = o; } }
;     LDS_WAIT(); asm volatile("" ::: "memory");
.Lcve_pA5e:
	s_waitcnt vmcnt(4)
	v_pk_mul_f32 v[56:57], v[56:57], s[40:41] op_sel_hi:[1,0]
	v_pk_mul_f32 v[58:59], v[58:59], s[40:41] op_sel_hi:[1,0]
	ds_write2_b32 v128, v56, v57 offset1:1
	ds_write2_b32 v128, v58, v59 offset0:2 offset1:3
	v_pk_mul_f32 v[60:61], v[60:61], s[40:41] op_sel_hi:[1,0]
	v_pk_mul_f32 v[62:63], v[62:63], s[40:41] op_sel_hi:[1,0]
	ds_write2_b32 v129, v60, v61 offset1:1
	ds_write2_b32 v129, v62, v63 offset0:2 offset1:3
	v_pk_mul_f32 v[64:65], v[64:65], s[40:41] op_sel_hi:[1,0]
	v_pk_mul_f32 v[66:67], v[66:67], s[40:41] op_sel_hi:[1,0]
	ds_write2_b32 v130, v64, v65 offset1:1
	ds_write2_b32 v130, v66, v67 offset0:2 offset1:3
	v_pk_mul_f32 v[68:69], v[68:69], s[40:41] op_sel_hi:[1,0]
	v_pk_mul_f32 v[70:71], v[70:71], s[40:41] op_sel_hi:[1,0]
	ds_write2_b32 v131, v68, v69 offset1:1
	ds_write2_b32 v131, v70, v71 offset0:2 offset1:3
	v_pk_mul_f32 v[72:73], v[72:73], s[40:41] op_sel_hi:[1,0]
	v_pk_mul_f32 v[74:75], v[74:75], s[40:41] op_sel_hi:[1,0]
	ds_write2_b32 v132, v72, v73 offset1:1
	ds_write2_b32 v132, v74, v75 offset0:2 offset1:3
	v_pk_mul_f32 v[76:77], v[76:77], s[40:41] op_sel_hi:[1,0]
	v_pk_mul_f32 v[78:79], v[78:79], s[40:41] op_sel_hi:[1,0]
	ds_write2_b32 v133, v76, v77 offset1:1
	ds_write2_b32 v133, v78, v79 offset0:2 offset1:3
	v_pk_mul_f32 v[80:81], v[80:81], s[40:41] op_sel_hi:[1,0]
	v_pk_mul_f32 v[82:83], v[82:83], s[40:41] op_sel_hi:[1,0]
	ds_write2_b32 v134, v80, v81 offset1:1
	ds_write2_b32 v134, v82, v83 offset0:2 offset1:3
	v_pk_mul_f32 v[84:85], v[84:85], s[40:41] op_sel_hi:[1,0]
	v_pk_mul_f32 v[86:87], v[86:87], s[40:41] op_sel_hi:[1,0]
	ds_write2_b32 v135, v84, v85 offset1:1
	ds_write2_b32 v135, v86, v87 offset0:2 offset1:3
	s_waitcnt lgkmcnt(0)
	ds_read2_b32 v[88:89], v9 offset0:0 offset1:33
	ds_read2_b32 v[90:91], v9 offset0:66 offset1:99
	ds_read2_b32 v[92:93], v9 offset0:132 offset1:165
	ds_read2_b32 v[94:95], v9 offset0:198 offset1:231
	ds_read2_b32 v[96:97], v9 offset0:8 offset1:41
	ds_read2_b32 v[98:99], v9 offset0:74 offset1:107
	ds_read2_b32 v[100:101], v9 offset0:140 offset1:173
	ds_read2_b32 v[102:103], v9 offset0:206 offset1:239
	ds_read2_b32 v[104:105], v9 offset0:16 offset1:49
	ds_read2_b32 v[106:107], v9 offset0:82 offset1:115
	ds_read2_b32 v[108:109], v9 offset0:148 offset1:181
	ds_read2_b32 v[110:111], v9 offset0:214 offset1:247
	ds_read2_b32 v[112:113], v9 offset0:24 offset1:57
	ds_read2_b32 v[114:115], v9 offset0:90 offset1:123
	ds_read2_b32 v[116:117], v9 offset0:156 offset1:189
	ds_read2_b32 v[118:119], v9 offset0:222 offset1:255
	s_waitcnt lgkmcnt(12)
	v_cvt_pk_fp8_f32 v120, v88, v89
	v_cvt_pk_fp8_f32 v121, v92, v93
	v_cvt_pk_fp8_f32 v120, v90, v91 op_sel:[0,0,1]
	v_cvt_pk_fp8_f32 v121, v94, v95 op_sel:[0,0,1]
	s_waitcnt lgkmcnt(8)
	v_cvt_pk_fp8_f32 v122, v96, v97
	v_cvt_pk_fp8_f32 v123, v100, v101
	v_cvt_pk_fp8_f32 v122, v98, v99 op_sel:[0,0,1]
	v_cvt_pk_fp8_f32 v123, v102, v103 op_sel:[0,0,1]
	s_waitcnt lgkmcnt(4)
	v_cvt_pk_fp8_f32 v124, v104, v105
	v_cvt_pk_fp8_f32 v125, v108, v109
	v_cvt_pk_fp8_f32 v124, v106, v107 op_sel:[0,0,1]
	v_cvt_pk_fp8_f32 v125, v110, v111 op_sel:[0,0,1]
	s_waitcnt lgkmcnt(0)
	v_cvt_pk_fp8_f32 v126, v112, v113
	v_cvt_pk_fp8_f32 v127, v116, v117
	v_cvt_pk_fp8_f32 v126, v114, v115 op_sel:[0,0,1]
	v_cvt_pk_fp8_f32 v127, v118, v119 op_sel:[0,0,1]
	s_cmp_eq_u32 s38, 0
	s_cbranch_scc0 .Lcve_pB6d
	global_store_dwordx2 v19, v[120:121], s[36:37]
	global_store_dwordx2 v20, v[122:123], s[36:37]
	global_store_dwordx2 v21, v[124:125], s[36:37]
	global_store_dwordx2 v22, v[126:127], s[36:37]
	s_branch .Lcve_pB6e

; #define LAS __attribute__((address_space(3)))
; __device__ __forceinline__ unsigned cvt_pk_bf16(float lo, float hi) { unsigned r; asm volatile("v_cvt_pk_bf16_f32 %0, %1, %2" : "=v"(r) : "v"(lo), "v"(hi)); return r; }
; __device__ __forceinline__ unsigned cvt4_fp8(float a, float b, float c, float d) { unsigned w = __builtin_amdgcn_cvt_pk_fp8_f32(a, b, 0u, false); return (unsigned)__builtin_amdgcn_cvt_pk_fp8_f32(c, d, (int)w, true); }
; #define LDS_WAIT() asm volatile("s_waitcnt lgkmcnt(0)" ::: "memory")
;     ...
;         for (int i = 0; i < 8; ++i) { const int kk = 8 * i + r8; const float m = kscale ? sc * kscale[k0 + kk] : sc;
;             scr[kk * 33 + c4 + 0] = v[i][0] * m; scr[kk * 33 + c4 + 1] = v[i][1] * m; scr[kk * 33 + c4 + 2] = v[i][2] * m; scr[kk * 33 + c4 + 3] = v[i][3] * m; }
;     } else {
;         const float* src; int ld; float sc; f(n0 + (lane & 31), src, ld, sc); sc *= mul;
; #pragma unroll 8
;         for (int i = 0; i < 32; ++i) { const int kk = 2 * i + (lane >> 5); float v = src[(size_t)(k0 + kk) * ld] * sc; if (kscale) v *= kscale[k0 + kk]; scr[kk * 33 + (lane & 31)] = v; }
;     }
;     LDS_WAIT(); asm volatile("" ::: "memory");
;     const int c = lane & 7;
; #pragma unroll
;     for (int j = 0; j < 4; ++j) { const int n = (lane >> 3) + 8 * j; const LAS float* s = scr + (8 * c) * 33 + n;
;         if constexpr (F8OUT) {
;             u32x2 o; o.x = cvt4_fp8(s[0 * 33], s[1 * 33], s[2 * 33], s[3 * 33]); o.y = cvt4_fp8(s[4 * 33], s[5 * 33], s[6 * 33], s[7 * 33]);
;             *(u32x2*)((unsigned char*)WT + (size_t)(n0 + n) * K + k0 + 8 * c) = o;
;         } else {
;             u32x4 o; o.x = cvt_pk_bf16(s[0 * 33], s[1 * 33]); o.y = cvt_pk_bf16(s[2 * 33], s[3 * 33]); o.z = cvt_pk_bf16(s[4 * 33], s[5 * 33]); o.w = cvt_pk_bf16(s[6 * 33], s[7 * 33]);
;             *(u32x4*)(WT + (size_t)(n0 + n) * K + k0 + 8 * c) = o; } }
;     LDS_WAIT(); asm volatile("" ::: "memory");
.Lcve_iA8e:
	s_waitcnt vmcnt(0)
	v_pk_mul_f32 v[24:25], v[24:25], s[32:33] op_sel_hi:[1,0]
	v_pk_mul_f32 v[26:27], v[26:27], s[32:33] op_sel_hi:[1,0]
	ds_write2_b32 v128, v24, v25 offset1:1
	ds_write2_b32 v128, v26, v27 offset0:2 offset1:3
	v_pk_mul_f32 v[28:29], v[28:29], s[32:33] op_sel_hi:[1,0]
	v_pk_mul_f32 v[30:31], v[30:31], s[32:33] op_sel_hi:[1,0]
	ds_write2_b32 v129, v28, v29 offset1:1
	ds_write2_b32 v129, v30, v31 offset0:2 offset1:3
	v_pk_mul_f32 v[32:33], v[32:33], s[32:33] op_sel_hi:[1,0]
	v_pk_mul_f32 v[34:35], v[34:35], s[32:33] op_sel_hi:[1,0]
	ds_write2_b32 v130, v32, v33 offset1:1
	ds_write2_b32 v130, v34, v35 offset0:2 offset1:3
	v_pk_mul_f32 v[36:37], v[36:37], s[32:33] op_sel_hi:[1,0]
	v_pk_mul_f32 v[38:39], v[38:39], s[32:33] op_sel_hi:[1,0]
	ds_write2_b32 v131, v36, v37 offset1:1
	ds_write2_b32 v131, v38, v39 offset0:2 offset1:3
	v_pk_mul_f32 v[40:41], v[40:41], s[32:33] op_sel_hi:[1,0]
	v_pk_mul_f32 v[42:43], v[42:43], s[32:33] op_sel_hi:[1,0]
	ds_write2_b32 v132, v40, v41 offset1:1
	ds_write2_b32 v132, v42, v43 offset0:2 offset1:3
	v_pk_mul_f32 v[44:45], v[44:45], s[32:33] op_sel_hi:[1,0]
	v_pk_mul_f32 v[46:47], v[46:47], s[32:33] op_sel_hi:[1,0]
	ds_write2_b32 v133, v44, v45 offset1:1
	ds_write2_b32 v133, v46, v47 offset0:2 offset1:3
	v_pk_mul_f32 v[48:49], v[48:49], s[32:33] op_sel_hi:[1,0]
	v_pk_mul_f32 v[50:51], v[50:51], s[32:33] op_sel_hi:[1,0]
	ds_write2_b32 v134, v48, v49 offset1:1
	ds_write2_b32 v134, v50, v51 offset0:2 offset1:3
	v_pk_mul_f32 v[52:53], v[52:53], s[32:33] op_sel_hi:[1,0]
	v_pk_mul_f32 v[54:55], v[54:55], s[32:33] op_sel_hi:[1,0]
	ds_write2_b32 v135, v52, v53 offset1:1
	ds_write2_b32 v135, v54, v55 offset0:2 offset1:3
	s_waitcnt lgkmcnt(0)
	ds_read2_b32 v[88:89], v9 offset0:0 offset1:33
	ds_read2_b32 v[90:91], v9 offset0:66 offset1:99
	ds_read2_b32 v[92:93], v9 offset0:132 offset1:165
	ds_read2_b32 v[94:95], v9 offset0:198 offset1:231
	ds_read2_b32 v[96:97], v9 offset0:8 offset1:41
	ds_read2_b32 v[98:99], v9 offset0:74 offset1:107
	ds_read2_b32 v[100:101], v9 offset0:140 offset1:173
	ds_read2_b32 v[102:103], v9 offset0:206 offset1:239
	ds_read2_b32 v[104:105], v9 offset0:16 offset1:49
	ds_read2_b32 v[106:107], v9 offset0:82 offset1:115
	ds_read2_b32 v[108:109], v9 offset0:148 offset1:181
	ds_read2_b32 v[110:111], v9 offset0:214 offset1:247
	ds_read2_b32 v[112:113], v9 offset0:24 offset1:57
	ds_read2_b32 v[114:115], v9 offset0:90 offset1:123
	ds_read2_b32 v[116:117], v9 offset0:156 offset1:189
	ds_read2_b32 v[118:119], v9 offset0:222 offset1:255
	s_waitcnt lgkmcnt(12)
	v_cvt_pk_fp8_f32 v120, v88, v89
	v_cvt_pk_fp8_f32 v121, v92, v93
	v_cvt_pk_fp8_f32 v120, v90, v91 op_sel:[0,0,1]
	v_cvt_pk_fp8_f32 v121, v94, v95 op_sel:[0,0,1]
	s_waitcnt lgkmcnt(8)
	v_cvt_pk_fp8_f32 v122, v96, v97
	v_cvt_pk_fp8_f32 v123, v100, v101
	v_cvt_pk_fp8_f32 v122, v98, v99 op_sel:[0,0,1]
	v_cvt_pk_fp8_f32 v123, v102, v103 op_sel:[0,0,1]
	s_waitcnt lgkmcnt(4)
	v_cvt_pk_fp8_f32 v124, v104, v105
	v_cvt_pk_fp8_f32 v125, v108, v109
	v_cvt_pk_fp8_f32 v124, v106, v107 op_sel:[0,0,1]
	v_cvt_pk_fp8_f32 v125, v110, v111 op_sel:[0,0,1]
	s_waitcnt lgkmcnt(0)
	v_cvt_pk_fp8_f32 v126, v112, v113
	v_cvt_pk_fp8_f32 v127, v116, v117
	v_cvt_pk_fp8_f32 v126, v114, v115 op_sel:[0,0,1]
	v_cvt_pk_fp8_f32 v127, v118, v119 op_sel:[0,0,1]
	s_cmp_eq_u32 s30, 0
	s_cbranch_scc0 .Lcve_pA9d
	global_store_dwordx2 v19, v[120:121], s[28:29]
	global_store_dwordx2 v20, v[122:123], s[28:29]
	global_store_dwordx2 v21, v[124:125], s[28:29]
	global_store_dwordx2 v22, v[126:127], s[28:29]
	s_branch .Lcve_pA9e
